# grid barrier: all workgroups poll the top generation word directly; per-XCD generation atomic dropped
# baseline (speedup 1.0000x reference)
.LBB0_1029:
	s_or_b64 exec, exec, s[2:3]
	v_cvt_f32_u32_e32 v4, v2
	s_waitcnt vmcnt(0)
	v_readfirstlane_b32 s2, v3
	v_sub_u32_e32 v3, 0, v2
	v_rcp_iflag_f32_e32 v4, v4
	v_add_u32_e32 v5, s2, v1
	v_mul_f32_e32 v4, 0x4f7ffffe, v4
	v_cvt_u32_f32_e32 v4, v4
	v_mul_lo_u32 v1, v3, v4
	v_mul_hi_u32 v1, v4, v1
	v_add_u32_e32 v1, v4, v1
	v_mul_hi_u32 v1, v5, v1
	v_mul_lo_u32 v3, v1, v2
	v_sub_u32_e32 v3, v5, v3
	v_add_u32_e32 v4, 1, v1
	v_cmp_ge_u32_e32 vcc, v3, v2
	s_nop 1
	v_cndmask_b32_e32 v1, v1, v4, vcc
	v_sub_u32_e32 v4, v3, v2
	v_cndmask_b32_e32 v3, v3, v4, vcc
	v_add_u32_e32 v4, 1, v1
	v_cmp_ge_u32_e32 vcc, v3, v2
	v_add_u32_e32 v3, 1, v5
	s_nop 0
	v_cndmask_b32_e32 v1, v1, v4, vcc
	v_mul_lo_u32 v4, v2, v1
	v_add_u32_e32 v2, v4, v2
	v_cmp_ne_u32_e32 vcc, v3, v2
	s_and_saveexec_b64 s[2:3], vcc
	s_xor_b64 s[2:3], exec, s[2:3]
	s_cbranch_execz .LBB0_1043
	v_readlane_b32 s4, v253, 18
	v_readlane_b32 s5, v253, 19
	s_waitcnt lgkmcnt(0)
	s_nop 3
	global_load_dword v0, v195, s[4:5] sc1
	s_waitcnt vmcnt(0)
	v_cmp_eq_u32_e32 vcc, v0, v1
	s_and_saveexec_b64 s[4:5], vcc
	s_cbranch_execz .LBB0_1042
	s_mov_b32 s19, 1
	s_mov_b64 s[6:7], 0
	s_branch .LBB0_1033

.LBB0_1037:
	v_readlane_b32 s10, v253, 18
	v_readlane_b32 s11, v253, 19
	s_add_i32 s19, s19, 1
	s_mov_b64 s[12:13], -1
	s_nop 2
	global_load_dword v0, v195, s[10:11] sc1
	s_waitcnt vmcnt(0)
	v_cmp_ne_u32_e32 vcc, v0, v1
	s_orn2_b64 s[10:11], vcc, exec
	s_branch .LBB0_1032

.LBB0_1060:
	s_or_b64 exec, exec, s[2:3]
	s_mov_b64 s[2:3], exec
	v_mbcnt_lo_u32_b32 v0, s2, 0
	v_mbcnt_hi_u32_b32 v0, s3, v0
	v_cmp_eq_u32_e32 vcc, 0, v0
	s_waitcnt vmcnt(0)
	buffer_inv sc1
	s_and_saveexec_b64 s[4:5], vcc
	s_cbranch_execz .LBB0_1062
.LBB0_1062:
	s_or_b64 exec, exec, s[4:5]
	s_waitcnt vmcnt(0)
